# scan: sQt/sKt/sVT double buffered by step parity so the end-of-step barrier of emitting steps is removed (waves 4-7 stage chunk s+1 while waves 0-3 finish AV + state of chunk s)
# baseline (speedup 1.0000x reference)
.LBB0_1144:
	s_ashr_i32 s5, s85, 2
	s_lshl_b32 s7, s85, 6
	s_lshl_b32 s6, s5, 8
	s_and_b32 s10, s7, 0x80
	s_or_b32 s6, s6, s10
	s_and_b32 s4, s85, 1
	s_bfe_i32 s8, s85, 0x10000
	s_ashr_i32 s12, s85, 4
	s_mul_hi_i32 s7, s6, 0x4200
	s_mulk_i32 s6, 0x4200
	s_and_b32 s11, s5, 3
	s_add_u32 s6, s56, s6
	s_addc_u32 s7, s57, s7
	s_cmp_eq_u32 s4, 0
	s_cselect_b64 s[4:5], -1, 0
	v_mov_b32_e32 v3, v148
	s_and_b64 s[14:15], s[4:5], exec
	s_mov_b32 s9, 0xc400000
	s_barrier
	s_cselect_b32 s9, s9, 0x10600000
	v_ashrrev_i32_e32 v14, 6, v3
	s_mov_b32 s13, 0x14800000
	v_add_u32_e32 v0, -4, v14
	s_cselect_b32 s13, s13, 0x1c800000
	s_cselect_b32 s86, 63, 0
	s_add_u32 s70, s54, s9
	v_lshrrev_b32_e32 v15, 1, v0
	v_and_b32_e32 v16, 1, v14
	s_addc_u32 s71, s55, 0
	v_cmp_gt_u32_e32 vcc, v16, v15
	s_add_u32 s13, s54, s13
	s_addc_u32 s14, s55, 0
	v_cndmask_b32_e64 v0, 0, 1, vcc
	v_cmp_lt_u32_e32 vcc, v16, v15
	s_lshl_b32 s87, s12, 8
	s_and_b32 s8, s8, 0xc0
	v_cndmask_b32_e64 v4, 0, 1, vcc
	s_add_i32 s87, s87, 0x10000
	v_cndmask_b32_e64 v17, v4, v0, s[4:5]
	s_or_b32 s15, s87, s8
	v_lshlrev_b32_e32 v4, 2, v3
	s_lshl_b32 s16, s8, 1
	s_or_b32 s8, s15, s86
	v_ashrrev_i32_e32 v149, 4, v3
	v_lshlrev_b32_e32 v0, 3, v3
	v_and_b32_e32 v21, 4, v4
	s_ashr_i32 s9, s8, 31
	v_and_b32_e32 v22, 0x78, v0
	v_add_u32_e32 v4, s15, v149
	v_ashrrev_i32_e32 v5, 31, v4
	v_lshl_or_b32 v136, s11, 7, v22
	s_lshl_b64 s[8:9], s[8:9], 10
	v_lshlrev_b64 v[4:5], 10, v[4:5]
	s_waitcnt vmcnt(11)
	v_lshlrev_b32_e32 v8, 1, v136
	s_add_u32 s8, s70, s8
	v_or_b32_e32 v4, v4, v8
	s_addc_u32 s9, s71, s9
	s_lshl_b32 s17, s11, 8
	v_add_u32_e32 v23, 0x200, v3
	s_waitcnt vmcnt(5)
	v_lshl_add_u64 v[6:7], s[76:77], 0, v[4:5]
	s_add_u32 s8, s8, s17
	v_ashrrev_i32_e32 v172, 4, v23
	s_addc_u32 s9, s9, 0
	v_lshlrev_b32_e32 v0, 1, v22
	global_load_dwordx4 v[138:141], v[6:7], off
	global_load_dwordx4 v[142:145], v0, s[8:9]
	v_add_u32_e32 v6, s15, v172
	v_ashrrev_i32_e32 v7, 31, v6
	v_lshlrev_b64 v[6:7], 10, v[6:7]
	v_lshl_add_u64 v[4:5], s[70:71], 0, v[4:5]
	v_or_b32_e32 v6, v6, v8
	v_lshl_add_u64 v[8:9], s[76:77], 0, v[6:7]
	global_load_dwordx4 v[156:159], v[4:5], off
	global_load_dwordx4 v[160:163], v[8:9], off
	v_lshl_add_u64 v[4:5], s[70:71], 0, v[6:7]
	global_load_dwordx4 v[164:167], v[4:5], off
	v_ashrrev_i32_e32 v12, 3, v3
	v_mov_b64_e32 v[4:5], s[6:7]
	v_mad_i64_i32 v[6:7], s[6:7], v12, s33, v[4:5]
	v_add_u32_e32 v12, 64, v12
	s_or_b32 s48, s16, 0x4000
	v_lshlrev_b32_e32 v24, 4, v3
	v_mad_i64_i32 v[4:5], s[6:7], v12, s33, v[4:5]
	v_lshl_add_u64 v[8:9], v[6:7], 0, s[48:49]
	v_and_b32_e32 v10, 0x70, v24
	v_mov_b32_e32 v11, v1
	v_lshl_add_u64 v[12:13], v[4:5], 0, s[48:49]
	v_lshl_add_u64 v[8:9], v[8:9], 0, v[10:11]
	v_lshl_add_u64 v[12:13], v[12:13], 0, v[10:11]
	global_load_dwordx4 v[128:131], v[8:9], off
	global_load_dwordx4 v[132:135], v[12:13], off
	v_ashrrev_i32_e32 v8, 7, v3
	v_lshlrev_b32_e32 v9, 1, v149
	v_lshrrev_b32_e32 v12, 1, v21
	v_and_b32_e32 v25, 14, v9
	v_lshlrev_b32_e32 v9, 7, v22
	v_xor_b32_e32 v13, v12, v8
	v_lshl_add_u32 v26, v13, 4, v9
	v_or_b32_e32 v13, 2, v22
	v_or_b32_e32 v29, 3, v22
	v_or_b32_e32 v32, 8, v22
	v_or_b32_e32 v35, 9, v22
	v_or_b32_e32 v38, 10, v22
	v_or_b32_e32 v22, 11, v22
	v_lshlrev_b32_e32 v27, 7, v13
	v_lshrrev_b32_e32 v13, 1, v13
	v_lshlrev_b32_e32 v30, 7, v29
	v_lshrrev_b32_e32 v29, 1, v29
	v_lshlrev_b32_e32 v33, 7, v32
	v_lshrrev_b32_e32 v32, 1, v32
	v_lshlrev_b32_e32 v36, 7, v35
	v_lshrrev_b32_e32 v35, 1, v35
	v_lshlrev_b32_e32 v39, 7, v38
	v_lshrrev_b32_e32 v38, 1, v38
	v_lshlrev_b32_e32 v41, 7, v22
	v_lshrrev_b32_e32 v22, 1, v22
	v_bitop3_b32 v28, v13, v8, 3 bitop3:0x6c
	v_bitop3_b32 v31, v29, v8, 3 bitop3:0x6c
	v_bitop3_b32 v34, v32, v8, 6 bitop3:0x6c
	v_bitop3_b32 v37, v35, v8, 6 bitop3:0x6c
	v_bitop3_b32 v40, v38, v8, 7 bitop3:0x6c
	v_bitop3_b32 v8, v22, v8, 7 bitop3:0x6c
	v_xor_b32_e32 v43, v149, v3
	v_lshl_add_u32 v42, v8, 4, v41
	v_lshlrev_b32_e32 v8, 8, v149
	v_lshlrev_b32_e32 v43, 4, v43
	s_add_u32 s8, s70, s17
	v_and_or_b32 v173, v43, s84, v8
	v_ashrrev_i32_e32 v8, 7, v23
	s_addc_u32 s9, s71, 0
	v_lshl_add_u64 v[154:155], v[4:5], 0, v[10:11]
	s_lshl_b32 s88, s12, 13
	v_lshlrev_b32_e32 v4, 5, v3
	v_lshlrev_b32_e32 v5, 2, v21
	s_movk_i32 s12, 0xffc0
	v_xor_b32_e32 v12, v12, v8
	s_nop 0
	v_lshl_add_u32 v43, v12, 4, v9
	v_bitop3_b32 v9, v13, v8, 3 bitop3:0x6c
	v_add_u32_e32 v176, 0x16000, v4
	v_and_b32_e32 v4, 1, v17
	v_lshl_add_u32 v28, v28, 4, v27
	v_lshl_add_u32 v27, v9, 4, v27
	v_bitop3_b32 v9, v29, v8, 3 bitop3:0x6c
	v_cmp_eq_u32_e32 vcc, 1, v4
	v_lshl_add_u32 v29, v9, 4, v30
	v_bitop3_b32 v9, v32, v8, 6 bitop3:0x6c
	s_xor_b64 s[78:79], vcc, -1
	s_lshl_b32 s11, s11, 9
	v_lshl_add_u32 v31, v31, 4, v30
	v_lshl_add_u32 v30, v9, 4, v33
	v_bitop3_b32 v9, v35, v8, 6 bitop3:0x6c
	s_add_u32 s11, s13, s11
	v_and_b32_e32 v18, 31, v3
	v_lshl_add_u32 v32, v9, 4, v36
	v_bitop3_b32 v9, v38, v8, 7 bitop3:0x6c
	v_lshl_add_u64 v[146:147], s[8:9], 0, v[0:1]
	v_lshlrev_b32_e32 v0, 5, v14
	s_addc_u32 s12, s14, 0
	s_lshl_b32 s10, s10, 1
	v_lshrrev_b32_e32 v2, 5, v3
	v_bfe_u32 v19, v3, 5, 1
	v_bfe_u32 v20, v3, 1, 3
	v_lshl_add_u32 v34, v34, 4, v33
	v_lshl_add_u32 v33, v9, 4, v39
	v_xor_b32_e32 v9, v172, v3
	v_and_b32_e32 v35, 0xffffff80, v24
	v_bitop3_b32 v24, v24, s51, v3 bitop3:0x48
	v_cmp_gt_i32_e64 s[6:7], 16, v3
	v_lshl_add_u64 v[152:153], v[6:7], 0, v[10:11]
	v_and_b32_e32 v0, 0x60, v0
	v_lshlrev_b32_e32 v177, 8, v18
	v_and_b32_e32 v6, 15, v3
	v_lshlrev_b32_e32 v3, 1, v3
	s_add_u32 s10, s11, s10
	v_lshl_or_b32 v179, v16, 13, v177
	v_lshl_or_b32 v7, v16, 5, v18
	v_and_b32_e32 v16, 14, v3
	v_or_b32_e32 v3, v0, v18
	s_addc_u32 s11, s12, 0
	v_lshlrev_b32_e32 v0, 1, v0
	v_lshl_add_u64 v[4:5], s[10:11], 0, v[0:1]
	v_lshlrev_b32_e32 v0, 1, v18
	v_lshl_add_u64 v[4:5], v[4:5], 0, v[0:1]
	v_bitop3_b32 v0, v2, v6, 1 bitop3:0x6c
	v_lshlrev_b32_e32 v184, 4, v0
	v_bitop3_b32 v0, v19, v6, 2 bitop3:0x36
	v_lshlrev_b32_e32 v185, 4, v0
	v_bitop3_b32 v0, v19, v6, 4 bitop3:0x36
	v_lshlrev_b32_e32 v186, 4, v0
	v_bitop3_b32 v0, v19, v6, 6 bitop3:0x36
	v_lshlrev_b32_e32 v187, 4, v0
	v_bitop3_b32 v0, v19, v6, 8 bitop3:0x36
	v_bitop3_b32 v8, v22, v8, 7 bitop3:0x6c
	v_lshlrev_b32_e32 v188, 4, v0
	v_bitop3_b32 v0, v19, v6, 10 bitop3:0x36
	v_lshl_add_u32 v22, v8, 4, v41
	v_lshlrev_b32_e32 v8, 8, v172
	v_lshlrev_b32_e32 v9, 4, v9
	v_lshlrev_b32_e32 v189, 4, v0
	v_bitop3_b32 v0, v19, v6, 12 bitop3:0x36
	v_and_or_b32 v174, v9, s84, v8
	v_lshlrev_b32_e32 v8, 2, v19
	v_lshlrev_b32_e32 v190, 4, v0
	v_bitop3_b32 v0, v19, v6, 14 bitop3:0x36
	v_lshlrev_b32_e32 v191, 4, v0
	v_lshl_or_b32 v0, v15, 5, v8
	v_cmp_le_u32_e32 vcc, v7, v0
	v_lshlrev_b32_e32 v180, 7, v3
	v_lshrrev_b32_e32 v9, 3, v7
	v_cndmask_b32_e64 v3, 0, 1, vcc
	v_cmp_ge_u32_e32 vcc, v7, v0
	v_lshlrev_b32_e32 v8, 4, v9
	v_lshlrev_b32_e32 v181, 7, v18
	v_cndmask_b32_e64 v6, 0, 1, vcc
	v_cndmask_b32_e64 v3, v6, v3, s[4:5]
	v_and_b32_e32 v3, 1, v3
	v_cmp_eq_u32_e64 s[10:11], 1, v3
	v_lshlrev_b32_e32 v3, 7, v0
	v_lshlrev_b32_e32 v6, 5, v19
	v_bitop3_b32 v3, v3, v8, v6 bitop3:0xf6
	v_add_u32_e32 v17, 0x14000, v3
	v_or_b32_e32 v3, 1, v0
	v_cmp_gt_u32_e32 vcc, v7, v0
	v_lshl_add_u32 v37, v37, 4, v36
	v_lshl_add_u32 v40, v40, 4, v39
	v_cndmask_b32_e64 v10, 0, 1, vcc
	v_cmp_le_u32_e32 vcc, v7, v3
	v_lshlrev_b32_e32 v3, 7, v3
	v_bitop3_b32 v3, v3, v8, v6 bitop3:0xf6
	v_cndmask_b32_e64 v11, 0, 1, vcc
	v_cndmask_b32_e64 v10, v10, v11, s[4:5]
	v_add_u32_e32 v18, 0x14000, v3
	v_or_b32_e32 v3, 2, v0
	v_and_b32_e32 v10, 1, v10
	v_cmp_le_u32_e32 vcc, v7, v3
	v_cmp_eq_u32_e64 s[12:13], 1, v10
	v_lshlrev_b32_e32 v23, 1, v172
	v_cndmask_b32_e64 v10, 0, 1, vcc
	v_cmp_ge_u32_e32 vcc, v7, v3
	v_and_b32_e32 v23, 14, v23
	v_cmp_gt_i32_e64 s[8:9], 4, v14
	v_cndmask_b32_e64 v11, 0, 1, vcc
	v_cndmask_b32_e64 v10, v11, v10, s[4:5]
	v_and_b32_e32 v10, 1, v10
	v_cmp_eq_u32_e64 s[14:15], 1, v10
	v_lshrrev_b32_e32 v10, 1, v3
	v_bitop3_b32 v10, v10, v9, 3 bitop3:0x6c
	v_lshlrev_b32_e32 v10, 4, v10
	v_lshl_or_b32 v3, v3, 7, v10
	v_add_u32_e32 v21, 0x14000, v3
	v_or_b32_e32 v3, 3, v0
	v_cmp_le_u32_e32 vcc, v7, v3
	v_lshl_or_b32 v178, v15, 13, v177
	v_mov_b32_e32 v14, v1
	v_cndmask_b32_e64 v10, 0, 1, vcc
	v_cmp_ge_u32_e32 vcc, v7, v3
	v_mov_b32_e32 v15, v1
	v_lshl_or_b32 v183, v19, 4, v137
	v_cndmask_b32_e64 v11, 0, 1, vcc
	v_cndmask_b32_e64 v10, v11, v10, s[4:5]
	v_and_b32_e32 v10, 1, v10
	v_cmp_eq_u32_e64 s[16:17], 1, v10
	v_lshrrev_b32_e32 v10, 1, v3
	v_bitop3_b32 v10, v10, v9, 3 bitop3:0x6c
	v_lshlrev_b32_e32 v10, 4, v10
	v_lshl_or_b32 v3, v3, 7, v10
	v_add_u32_e32 v36, 0x14000, v3
	v_or_b32_e32 v3, 8, v0
	v_cmp_le_u32_e32 vcc, v7, v3
	v_mov_b32_e32 v12, v1
	v_mov_b32_e32 v13, v1
	v_cndmask_b32_e64 v10, 0, 1, vcc
	v_cmp_ge_u32_e32 vcc, v7, v3
	v_add_u32_e32 v197, v26, v25
	v_add_u32_e32 v198, v28, v25
	v_cndmask_b32_e64 v11, 0, 1, vcc
	v_cndmask_b32_e64 v10, v11, v10, s[4:5]
	v_and_b32_e32 v10, 1, v10
	v_cmp_eq_u32_e64 s[18:19], 1, v10
	v_lshrrev_b32_e32 v10, 1, v3
	v_bitop3_b32 v10, v10, v9, 6 bitop3:0x6c
	v_lshlrev_b32_e32 v10, 4, v10
	v_lshl_or_b32 v3, v3, 7, v10
	v_add_u32_e32 v38, 0x14000, v3
	v_or_b32_e32 v3, 9, v0
	v_cmp_le_u32_e32 vcc, v7, v3
	v_add_u32_e32 v199, v31, v25
	v_add_u32_e32 v200, v34, v25
	v_cndmask_b32_e64 v10, 0, 1, vcc
	v_cmp_ge_u32_e32 vcc, v7, v3
	v_add_u32_e32 v201, v37, v25
	v_add_u32_e32 v202, v40, v25
	v_cndmask_b32_e64 v11, 0, 1, vcc
	v_cndmask_b32_e64 v10, v11, v10, s[4:5]
	v_and_b32_e32 v10, 1, v10
	v_cmp_eq_u32_e64 s[20:21], 1, v10
	v_lshrrev_b32_e32 v10, 1, v3
	v_bitop3_b32 v10, v10, v9, 6 bitop3:0x6c
	v_lshlrev_b32_e32 v10, 4, v10
	v_lshl_or_b32 v3, v3, 7, v10
	v_add_u32_e32 v39, 0x14000, v3
	v_or_b32_e32 v3, 10, v0
	v_cmp_le_u32_e32 vcc, v7, v3
	v_add_u32_e32 v203, v42, v25
	v_add_u32_e32 v204, v43, v23
	v_cndmask_b32_e64 v10, 0, 1, vcc
	v_cmp_ge_u32_e32 vcc, v7, v3
	v_add_u32_e32 v205, v27, v23
	v_add_u32_e32 v206, v29, v23
	v_cndmask_b32_e64 v11, 0, 1, vcc
	v_cndmask_b32_e64 v10, v11, v10, s[4:5]
	v_and_b32_e32 v10, 1, v10
	v_cmp_eq_u32_e64 s[22:23], 1, v10
	v_lshrrev_b32_e32 v10, 1, v3
	v_bitop3_b32 v10, v10, v9, 7 bitop3:0x6c
	v_lshlrev_b32_e32 v10, 4, v10
	v_lshl_or_b32 v3, v3, 7, v10
	v_add_u32_e32 v41, 0x14000, v3
	v_or_b32_e32 v3, 11, v0
	v_cmp_le_u32_e32 vcc, v7, v3
	v_add_u32_e32 v207, v30, v23
	v_add_u32_e32 v208, v32, v23
	v_cndmask_b32_e64 v10, 0, 1, vcc
	v_cmp_ge_u32_e32 vcc, v7, v3
	v_add_u32_e32 v209, v33, v23
	v_add_u32_e32 v210, v22, v23
	v_cndmask_b32_e64 v11, 0, 1, vcc
	v_cndmask_b32_e64 v10, v11, v10, s[4:5]
	v_and_b32_e32 v10, 1, v10
	v_cmp_eq_u32_e64 s[24:25], 1, v10
	v_lshrrev_b32_e32 v10, 1, v3
	v_bitop3_b32 v10, v10, v9, 7 bitop3:0x6c
	v_lshlrev_b32_e32 v10, 4, v10
	v_lshl_or_b32 v3, v3, 7, v10
	v_add_u32_e32 v44, 0x14000, v3
	v_or_b32_e32 v3, 16, v0
	v_cmp_le_u32_e32 vcc, v7, v3
	v_add_u32_e32 v211, v35, v24
	v_add_u32_e32 v212, v17, v16
	v_cndmask_b32_e64 v10, 0, 1, vcc
	v_cmp_ge_u32_e32 vcc, v7, v3
	v_lshlrev_b32_e32 v3, 7, v3
	v_bitop3_b32 v3, v3, v8, v6 bitop3:0xf6
	v_cndmask_b32_e64 v11, 0, 1, vcc
	v_cndmask_b32_e64 v10, v11, v10, s[4:5]
	v_add_u32_e32 v45, 0x14000, v3
	v_or_b32_e32 v3, 17, v0
	v_and_b32_e32 v10, 1, v10
	v_cmp_le_u32_e32 vcc, v7, v3
	v_cmp_eq_u32_e64 s[26:27], 1, v10
	v_add_u32_e32 v213, v18, v16
	v_cndmask_b32_e64 v10, 0, 1, vcc
	v_cmp_ge_u32_e32 vcc, v7, v3
	v_lshlrev_b32_e32 v3, 7, v3
	v_bitop3_b32 v3, v3, v8, v6 bitop3:0xf6
	v_add_u32_e32 v46, 0x14000, v3
	v_or_b32_e32 v3, 18, v0
	v_cndmask_b32_e64 v11, 0, 1, vcc
	v_cmp_le_u32_e32 vcc, v7, v3
	v_cndmask_b32_e64 v10, v11, v10, s[4:5]
	v_and_b32_e32 v10, 1, v10
	v_cndmask_b32_e64 v6, 0, 1, vcc
	v_cmp_ge_u32_e32 vcc, v7, v3
	v_cmp_eq_u32_e64 s[28:29], 1, v10
	v_mov_b32_e32 v10, v1
	v_cndmask_b32_e64 v8, 0, 1, vcc
	v_cndmask_b32_e64 v6, v8, v6, s[4:5]
	v_and_b32_e32 v6, 1, v6
	v_cmp_eq_u32_e64 s[30:31], 1, v6
	v_lshrrev_b32_e32 v6, 1, v3
	v_bitop3_b32 v6, v6, v9, 3 bitop3:0x6c
	v_lshlrev_b32_e32 v6, 4, v6
	v_lshl_or_b32 v3, v3, 7, v6
	v_add_u32_e32 v47, 0x14000, v3
	v_or_b32_e32 v3, 19, v0
	v_cmp_le_u32_e32 vcc, v7, v3
	v_mov_b32_e32 v11, v1
	v_add_u32_e32 v214, v21, v16
	v_cndmask_b32_e64 v6, 0, 1, vcc
	v_cmp_ge_u32_e32 vcc, v7, v3
	v_add_u32_e32 v215, v36, v16
	v_add_u32_e32 v216, v38, v16
	v_cndmask_b32_e64 v8, 0, 1, vcc
	v_cndmask_b32_e64 v6, v8, v6, s[4:5]
	v_and_b32_e32 v6, 1, v6
	v_cmp_eq_u32_e64 s[34:35], 1, v6
	v_lshrrev_b32_e32 v6, 1, v3
	v_bitop3_b32 v6, v6, v9, 3 bitop3:0x6c
	v_lshlrev_b32_e32 v6, 4, v6
	v_lshl_or_b32 v3, v3, 7, v6
	v_add_u32_e32 v48, 0x14000, v3
	v_or_b32_e32 v3, 24, v0
	v_cmp_le_u32_e32 vcc, v7, v3
	v_add_u32_e32 v217, v39, v16
	v_add_u32_e32 v218, v41, v16
	v_cndmask_b32_e64 v6, 0, 1, vcc
	v_cmp_ge_u32_e32 vcc, v7, v3
	v_add_u32_e32 v219, v44, v16
	v_add_u32_e32 v220, v45, v16
	v_cndmask_b32_e64 v8, 0, 1, vcc
	v_cndmask_b32_e64 v6, v8, v6, s[4:5]
	v_and_b32_e32 v6, 1, v6
	v_cmp_eq_u32_e64 s[36:37], 1, v6
	v_lshrrev_b32_e32 v6, 1, v3
	v_bitop3_b32 v6, v6, v9, 6 bitop3:0x6c
	v_lshlrev_b32_e32 v6, 4, v6
	v_lshl_or_b32 v3, v3, 7, v6
	v_add_u32_e32 v49, 0x14000, v3
	v_or_b32_e32 v3, 25, v0
	v_cmp_le_u32_e32 vcc, v7, v3
	v_add_u32_e32 v221, v46, v16
	v_add_u32_e32 v222, v47, v16
	v_cndmask_b32_e64 v6, 0, 1, vcc
	v_cmp_ge_u32_e32 vcc, v7, v3
	v_add_u32_e32 v223, v48, v16
	v_add_u32_e32 v224, v49, v16
	v_cndmask_b32_e64 v8, 0, 1, vcc
	v_cndmask_b32_e64 v6, v8, v6, s[4:5]
	v_and_b32_e32 v6, 1, v6
	v_cmp_eq_u32_e64 s[38:39], 1, v6
	v_lshrrev_b32_e32 v6, 1, v3
	v_bitop3_b32 v6, v6, v9, 6 bitop3:0x6c
	v_lshlrev_b32_e32 v6, 4, v6
	v_lshl_or_b32 v3, v3, 7, v6
	v_add_u32_e32 v50, 0x14000, v3
	v_or_b32_e32 v3, 26, v0
	v_cmp_le_u32_e32 vcc, v7, v3
	v_or_b32_e32 v0, 27, v0
	v_add_u32_e32 v225, v50, v16
	v_cndmask_b32_e64 v6, 0, 1, vcc
	v_cmp_ge_u32_e32 vcc, v7, v3
	v_or_b32_e32 v182, 0x14000, v181
	s_waitcnt vmcnt(16)
	v_mov_b64_e32 v[170:171], 0
	v_cndmask_b32_e64 v8, 0, 1, vcc
	v_cndmask_b32_e64 v6, v8, v6, s[4:5]
	v_and_b32_e32 v6, 1, v6
	v_cmp_eq_u32_e64 s[40:41], 1, v6
	v_lshrrev_b32_e32 v6, 1, v3
	v_bitop3_b32 v6, v6, v9, 7 bitop3:0x6c
	v_lshlrev_b32_e32 v6, 4, v6
	v_lshl_or_b32 v3, v3, 7, v6
	v_cmp_le_u32_e32 vcc, v7, v0
	v_add_u32_e32 v51, 0x14000, v3
	v_mov_b32_e32 v8, v1
	v_cndmask_b32_e64 v3, 0, 1, vcc
	v_cmp_ge_u32_e32 vcc, v7, v0
	v_mov_b32_e32 v7, v1
	v_add_u32_e32 v226, v51, v16
	v_cndmask_b32_e64 v6, 0, 1, vcc
	v_cndmask_b32_e64 v3, v6, v3, s[4:5]
	v_and_b32_e32 v3, 1, v3
	v_cmp_eq_u32_e64 s[42:43], 1, v3
	v_lshrrev_b32_e32 v3, 1, v0
	v_bitop3_b32 v3, v3, v9, 7 bitop3:0x6c
	v_lshlrev_b32_e32 v3, 4, v3
	v_lshl_or_b32 v0, v0, 7, v3
	v_add_u32_e32 v52, 0x14000, v0
	v_bitop3_b32 v0, v2, v20, 1 bitop3:0x6c
	v_lshlrev_b32_e32 v192, 4, v0
	v_bitop3_b32 v0, v19, v20, 2 bitop3:0x36
	v_lshlrev_b32_e32 v193, 4, v0
	v_bitop3_b32 v0, v19, v20, 4 bitop3:0x36
	v_lshlrev_b32_e32 v195, 4, v0
	v_bitop3_b32 v0, v19, v20, 6 bitop3:0x36
	v_lshlrev_b32_e32 v196, 4, v0
	v_lshlrev_b32_e32 v0, 13, v19
	v_lshl_add_u64 v[168:169], v[4:5], 0, v[0:1]
	v_mov_b32_e32 v0, v1
	v_mov_b32_e32 v2, v1
	v_mov_b32_e32 v3, v1
	v_mov_b32_e32 v4, v1
	v_mov_b32_e32 v5, v1
	v_mov_b32_e32 v6, v1
	v_mov_b32_e32 v9, v1
	v_add_u32_e32 v227, v52, v16
	v_mov_b64_e32 v[30:31], v[14:15]
	v_mov_b64_e32 v[46:47], v[14:15]
	v_mov_b64_e32 v[62:63], v[14:15]
	v_mov_b64_e32 v[78:79], v[14:15]
	s_movk_i32 s89, 0x82
	v_mov_b64_e32 v[28:29], v[12:13]
	v_mov_b64_e32 v[26:27], v[10:11]
	v_mov_b64_e32 v[24:25], v[8:9]
	v_mov_b64_e32 v[22:23], v[6:7]
	v_mov_b64_e32 v[20:21], v[4:5]
	v_mov_b64_e32 v[18:19], v[2:3]
	v_mov_b64_e32 v[16:17], v[0:1]
	v_mov_b64_e32 v[44:45], v[12:13]
	v_mov_b64_e32 v[42:43], v[10:11]
	v_mov_b64_e32 v[40:41], v[8:9]
	v_mov_b64_e32 v[38:39], v[6:7]
	v_mov_b64_e32 v[36:37], v[4:5]
	v_mov_b64_e32 v[34:35], v[2:3]
	v_mov_b64_e32 v[32:33], v[0:1]
	v_mov_b64_e32 v[60:61], v[12:13]
	v_mov_b64_e32 v[58:59], v[10:11]
	v_mov_b64_e32 v[56:57], v[8:9]
	v_mov_b64_e32 v[54:55], v[6:7]
	v_mov_b64_e32 v[52:53], v[4:5]
	v_mov_b64_e32 v[50:51], v[2:3]
	v_mov_b64_e32 v[48:49], v[0:1]
	v_mov_b64_e32 v[76:77], v[12:13]
	v_mov_b64_e32 v[74:75], v[10:11]
	v_mov_b64_e32 v[72:73], v[8:9]
	v_mov_b64_e32 v[70:71], v[6:7]
	v_mov_b64_e32 v[68:69], v[4:5]
	v_mov_b64_e32 v[66:67], v[2:3]
	v_mov_b64_e32 v[64:65], v[0:1]
	s_mov_b32 s81, s49
	v_mov_b64_e32 v[6:7], 0
	v_mov_b64_e32 v[8:9], 0
	v_mov_b64_e32 v[10:11], 0
	v_and_b32_e32 v113, 15, v148
	v_bfe_u32 v114, v148, 5, 1
	v_lshlrev_b32_e32 v115, 2, v113
	v_and_b32_e32 v115, 12, v115
	v_lshrrev_b32_e32 v116, 2, v113
	v_or_b32_e32 v115, v115, v116
	v_xor_b32_e32 v115, v115, v114
	v_xor_b32_e32 v116, 0, v115
	v_lshlrev_b32_e32 v184, 4, v116
	v_xor_b32_e32 v116, 2, v115
	v_lshlrev_b32_e32 v185, 4, v116
	v_xor_b32_e32 v116, 4, v115
	v_lshlrev_b32_e32 v186, 4, v116
	v_xor_b32_e32 v116, 6, v115
	v_lshlrev_b32_e32 v187, 4, v116
	v_xor_b32_e32 v116, 8, v115
	v_lshlrev_b32_e32 v188, 4, v116
	v_xor_b32_e32 v116, 10, v115
	v_lshlrev_b32_e32 v189, 4, v116
	v_xor_b32_e32 v116, 12, v115
	v_lshlrev_b32_e32 v190, 4, v116
	v_xor_b32_e32 v116, 14, v115
	v_lshlrev_b32_e32 v191, 4, v116
	v_lshlrev_b32_e32 v116, 2, v149
	v_and_b32_e32 v116, 12, v116
	v_bfe_u32 v117, v149, 2, 2
	v_or_b32_e32 v116, v116, v117
	v_and_b32_e32 v117, 14, v113
	v_xor_b32_e32 v116, v116, v117
	v_lshlrev_b32_e32 v116, 4, v116
	v_lshl_or_b32 v173, v149, 8, v116
	v_and_b32_e32 v117, 1, v113
	v_lshl_or_b32 v173, v117, 3, v173
	v_xor_b32_e32 v174, 16, v173
	v_mov_b64_e32 v[232:233], 0
	v_mov_b64_e32 v[234:235], 0
	v_and_b32_e32 v116, 3, v148
	v_bfe_u32 v117, v148, 2, 2
	v_bfe_u32 v118, v148, 4, 1
	v_and_b32_e32 v119, 1, v116
	v_lshl_or_b32 v119, v118, 1, v119
	v_lshlrev_b32_e32 v120, 1, v114
	v_xor_b32_e32 v119, v119, v120
	v_lshl_or_b32 v119, v117, 2, v119
	v_lshlrev_b32_e32 v119, 4, v119
	v_lshrrev_b32_e32 v120, 1, v116
	v_lshl_or_b32 v119, v120, 3, v119
	v_lshl_add_u32 v120, v114, 3, v117
	v_lshl_or_b32 v119, v120, 8, v119
	v_add_u32_e32 v197, 0x4000, v119
	v_xor_b32_e32 v198, 64, v197
	v_xor_b32_e32 v199, 0x80, v197
	v_xor_b32_e32 v200, 0xc0, v197
	v_xor_b32_e32 v201, 16, v197
	v_xor_b32_e32 v202, 16, v198
	v_xor_b32_e32 v203, 16, v199
	v_xor_b32_e32 v204, 16, v200
	v_add_u32_e32 v182, 0x4000, v182
	v_add_u32_e32 v176, 0x4000, v176
	v_add_u32_e32 v183, 0x4000, v183
	v_add_u32_e32 v212, 0x4000, v212
	v_add_u32_e32 v213, 0x4000, v213
	v_add_u32_e32 v214, 0x4000, v214
	v_add_u32_e32 v215, 0x4000, v215
	v_add_u32_e32 v216, 0x4000, v216
	v_add_u32_e32 v217, 0x4000, v217
	v_add_u32_e32 v218, 0x4000, v218
	v_add_u32_e32 v219, 0x4000, v219
	v_add_u32_e32 v220, 0x4000, v220
	v_add_u32_e32 v221, 0x4000, v221
	v_add_u32_e32 v222, 0x4000, v222
	v_add_u32_e32 v223, 0x4000, v223
	v_add_u32_e32 v224, 0x4000, v224
	v_add_u32_e32 v225, 0x4000, v225
	v_add_u32_e32 v226, 0x4000, v226
	v_add_u32_e32 v227, 0x4000, v227
	s_branch .LBB0_1146
.LBB0_1145:
	s_or_b64 exec, exec, s[44:45]
	s_add_i32 s89, s89, -1
	s_mov_b32 s81, s90
	s_and_b64 vcc, exec, s[82:83]
	s_cbranch_vccnz .Lscan_nob3
	s_barrier
.Lscan_nob3:
	s_cmp_lg_u32 s89, -2
	s_cbranch_scc0 .LBB0_1143
.LBB0_1146:
	s_and_b32 s32, s81, 1
	s_lshl_b32 s32, s32, 9
	s_mul_i32 s98, s32, 0x60
	s_cmp_gt_u32 s81, 3
	s_cselect_b64 s[82:83], -1, 0
	s_mov_b64 s[44:45], -1
	s_and_b64 vcc, exec, s[82:83]
	s_cbranch_vccnz .LBB0_1148
	s_add_i32 s48, s89, 0xffffff81
	s_and_b64 s[44:45], s[4:5], exec
	s_cselect_b32 s44, s81, s48
	s_lshl_b32 s44, s44, 6
	s_or_b32 s80, s44, s87
	s_mov_b64 s[44:45], 0

.LBB0_1150:
	v_add_u32_e32 v237, s98, v173
	v_add_u32_e32 v238, s98, v174
	v_add_u32_e32 v239, s98, v211
	s_waitcnt vmcnt(4)
	v_cvt_f32_f16_e32 v2, v156
	v_cvt_f32_f16_sdwa v3, v156 dst_sel:DWORD dst_unused:UNUSED_PAD src0_sel:WORD_1
	v_and_b32_e32 v5, 0xffff0000, v138
	v_exp_f32_e32 v114, v2
	v_exp_f32_e64 v116, -v2
	v_exp_f32_e32 v115, v3
	v_exp_f32_e64 v117, -v3
	v_lshlrev_b32_e32 v4, 16, v138
	v_lshlrev_b32_e32 v14, 16, v8
	v_and_b32_e32 v15, 0xffff0000, v8
	v_pk_mul_f32 v[114:115], v[114:115], v[14:15]
	v_pk_mul_f32 v[116:117], v[116:117], v[4:5]
	v_cvt_f32_f16_e32 v4, v157
	v_exp_f32_e32 v14, v4
	v_exp_f32_e64 v118, -v4
	v_cvt_f32_f16_sdwa v5, v157 dst_sel:DWORD dst_unused:UNUSED_PAD src0_sel:WORD_1
	v_lshlrev_b32_e32 v12, 16, v139
	v_exp_f32_e32 v15, v5
	v_exp_f32_e64 v119, -v5
	v_and_b32_e32 v13, 0xffff0000, v139
	v_lshlrev_b32_e32 v112, 16, v9
	v_and_b32_e32 v113, 0xffff0000, v9
	v_pk_mul_f32 v[120:121], v[14:15], v[112:113]
	v_pk_mul_f32 v[118:119], v[118:119], v[12:13]
	v_cvt_f32_f16_e32 v12, v158
	v_cvt_f32_f16_sdwa v13, v158 dst_sel:DWORD dst_unused:UNUSED_PAD src0_sel:WORD_1
	v_lshlrev_b32_e32 v14, 16, v140
	v_exp_f32_e32 v126, v12
	v_exp_f32_e64 v228, -v12
	v_exp_f32_e32 v127, v13
	v_exp_f32_e64 v229, -v13
	v_and_b32_e32 v15, 0xffff0000, v140
	v_lshlrev_b32_e32 v122, 16, v10
	v_and_b32_e32 v123, 0xffff0000, v10
	v_pk_mul_f32 v[122:123], v[126:127], v[122:123]
	v_pk_mul_f32 v[126:127], v[228:229], v[14:15]
	v_cvt_f32_f16_e32 v14, v159
	v_cvt_f32_f16_sdwa v15, v159 dst_sel:DWORD dst_unused:UNUSED_PAD src0_sel:WORD_1
	v_exp_f32_e32 v228, v14
	v_exp_f32_e64 v230, -v14
	v_exp_f32_e32 v229, v15
	v_exp_f32_e64 v231, -v15
	v_lshlrev_b32_e32 v112, 16, v141
	v_and_b32_e32 v113, 0xffff0000, v141
	v_lshlrev_b32_e32 v124, 16, v11
	v_and_b32_e32 v125, 0xffff0000, v11
	v_pk_mul_f32 v[124:125], v[228:229], v[124:125]
	v_pk_mul_f32 v[228:229], v[230:231], v[112:113]
	v_cvt_pk_bf16_f32 v112, v114, v115
	v_cvt_pk_bf16_f32 v115, v124, v125
	s_waitcnt vmcnt(2)
	v_cvt_f32_f16_e32 v15, v164
	v_cvt_f32_f16_sdwa v124, v164 dst_sel:DWORD dst_unused:UNUSED_PAD src0_sel:WORD_1
	v_cvt_pk_bf16_f32 v114, v122, v123
	v_cvt_pk_bf16_f32 v113, v120, v121
	v_exp_f32_e32 v120, v15
	v_exp_f32_e32 v121, v124
	v_cvt_pk_bf16_f32 v116, v116, v117
	v_cvt_pk_bf16_f32 v117, v118, v119
	v_exp_f32_e64 v122, -v15
	v_cvt_pk_bf16_f32 v118, v126, v127
	v_cvt_pk_bf16_f32 v119, v228, v229
	ds_write_b64 v237, v[112:113] offset:0
	ds_write_b64 v238, v[114:115] offset:0
	ds_write_b64 v237, v[116:117] offset:16384
	ds_write_b64 v238, v[118:119] offset:16384
	v_lshlrev_b32_e32 v116, 16, v232
	v_and_b32_e32 v117, 0xffff0000, v232
	v_pk_mul_f32 v[116:117], v[120:121], v[116:117]
	v_exp_f32_e64 v123, -v124
	v_lshlrev_b32_e32 v112, 16, v160
	v_and_b32_e32 v113, 0xffff0000, v160
	v_pk_mul_f32 v[120:121], v[122:123], v[112:113]
	v_cvt_f32_f16_e32 v123, v165
	v_cvt_f32_f16_sdwa v15, v165 dst_sel:DWORD dst_unused:UNUSED_PAD src0_sel:WORD_1
	v_exp_f32_e32 v112, v123
	v_exp_f32_e64 v122, -v123
	v_exp_f32_e32 v113, v15
	v_exp_f32_e64 v123, -v15
	v_lshlrev_b32_e32 v114, 16, v161
	v_and_b32_e32 v115, 0xffff0000, v161
	v_lshlrev_b32_e32 v118, 16, v233
	v_and_b32_e32 v119, 0xffff0000, v233
	v_pk_mul_f32 v[118:119], v[112:113], v[118:119]
	s_waitcnt vmcnt(2)
	v_cvt_f32_f16_e32 v15, v166
	v_cvt_f32_f16_sdwa v175, v166 dst_sel:DWORD dst_unused:UNUSED_PAD src0_sel:WORD_1
	v_lshlrev_b32_e32 v112, 16, v162
	v_exp_f32_e32 v228, v15
	v_exp_f32_e64 v230, -v15
	v_exp_f32_e32 v229, v175
	v_exp_f32_e64 v231, -v175
	v_and_b32_e32 v113, 0xffff0000, v162
	v_cvt_f32_f16_e32 v175, v167
	v_lshlrev_b32_e32 v124, 16, v234
	v_and_b32_e32 v125, 0xffff0000, v234
	v_pk_mul_f32 v[124:125], v[228:229], v[124:125]
	v_pk_mul_f32 v[228:229], v[230:231], v[112:113]
	v_cvt_f32_f16_sdwa v15, v167 dst_sel:DWORD dst_unused:UNUSED_PAD src0_sel:WORD_1
	v_exp_f32_e32 v112, v175
	v_exp_f32_e64 v230, -v175
	v_exp_f32_e32 v113, v15
	v_exp_f32_e64 v231, -v15
	v_pk_mul_f32 v[122:123], v[122:123], v[114:115]
	v_lshlrev_b32_e32 v114, 16, v163
	v_lshlrev_b32_e32 v126, 16, v235
	v_and_b32_e32 v127, 0xffff0000, v235
	v_and_b32_e32 v115, 0xffff0000, v163
	v_pk_mul_f32 v[126:127], v[112:113], v[126:127]
	v_pk_mul_f32 v[230:231], v[230:231], v[114:115]
	v_cvt_pk_bf16_f32 v112, v116, v117
	v_cvt_pk_bf16_f32 v113, v118, v119
	v_cvt_pk_bf16_f32 v114, v124, v125
	v_cvt_pk_bf16_f32 v115, v126, v127
	v_cvt_pk_bf16_f32 v116, v120, v121
	v_cvt_pk_bf16_f32 v117, v122, v123
	v_cvt_pk_bf16_f32 v118, v228, v229
	v_cvt_pk_bf16_f32 v119, v230, v231
	ds_write_b64 v237, v[112:113] offset:8192
	ds_write_b64 v238, v[114:115] offset:8192
	ds_write_b64 v237, v[116:117] offset:24576
	ds_write_b64 v238, v[118:119] offset:24576
	s_waitcnt vmcnt(1)
	ds_write_b128 v239, v[128:131] offset:32768
	s_waitcnt vmcnt(0)
	ds_write_b128 v239, v[132:135] offset:40960
	s_and_saveexec_b64 s[44:45], s[6:7]
	s_cbranch_execz .LBB0_1152
	v_cvt_f32_f16_e32 v112, v142
	v_cvt_f32_f16_sdwa v113, v142 dst_sel:DWORD dst_unused:UNUSED_PAD src0_sel:WORD_1
	v_cvt_f32_f16_e32 v114, v143
	v_cvt_f32_f16_sdwa v115, v143 dst_sel:DWORD dst_unused:UNUSED_PAD src0_sel:WORD_1
	v_cvt_f32_f16_e32 v2, v144
	v_cvt_f32_f16_sdwa v3, v144 dst_sel:DWORD dst_unused:UNUSED_PAD src0_sel:WORD_1
	v_cvt_f32_f16_e32 v4, v145
	v_cvt_f32_f16_sdwa v5, v145 dst_sel:DWORD dst_unused:UNUSED_PAD src0_sel:WORD_1
	v_exp_f32_e32 v112, v112
	v_exp_f32_e32 v113, v113
	v_exp_f32_e32 v114, v114
	v_exp_f32_e32 v115, v115
	v_exp_f32_e32 v2, v2
	v_exp_f32_e32 v3, v3
	v_exp_f32_e32 v4, v4
	v_exp_f32_e32 v5, v5
	v_add_u32_e32 v12, s32, v176
	ds_write_b128 v12, v[112:115]
	ds_write_b128 v12, v[2:5] offset:16

.Lscan_nodecay:
	s_andn2_b64 vcc, exec, s[82:83]
	s_cbranch_vccnz .LBB0_1172
	s_and_saveexec_b64 s[44:45], s[8:9]
	s_xor_b64 s[44:45], exec, s[44:45]
	s_cbranch_execz .LBB0_1165
	v_add3_u32 v0, v184, v177, s98
	ds_read_b128 v[12:15], v0
	ds_read_b128 v[112:115], v0 offset:8192
	v_add3_u32 v0, v185, v177, s98
	ds_read_b128 v[116:119], v0
	ds_read_b128 v[120:123], v0 offset:8192
	v_add3_u32 v0, v186, v177, s98
	ds_read_b128 v[124:127], v0
	v_cvt_pk_bf16_f32 v2, v64, v65
	v_cvt_pk_bf16_f32 v3, v66, v67
	v_cvt_pk_bf16_f32 v4, v68, v69
	v_cvt_pk_bf16_f32 v5, v70, v71
	s_waitcnt lgkmcnt(4)
	s_nop 0
	v_mfma_f32_32x32x16_bf16 v[80:95], v[2:5], v[12:15], 0
	ds_read_b128 v[12:15], v0 offset:8192
	s_waitcnt lgkmcnt(4)
	v_mfma_f32_32x32x16_bf16 v[96:111], v[2:5], v[112:115], 0
	v_add3_u32 v0, v187, v177, s98
	ds_read_b128 v[112:115], v0
	v_cvt_pk_bf16_f32 v2, v72, v73
	v_cvt_pk_bf16_f32 v3, v74, v75
	v_cvt_pk_bf16_f32 v4, v76, v77
	v_cvt_pk_bf16_f32 v5, v78, v79
	s_waitcnt lgkmcnt(4)
	s_nop 0
	v_mfma_f32_32x32x16_bf16 v[80:95], v[2:5], v[116:119], v[80:95]
	ds_read_b128 v[116:119], v0 offset:8192
	s_waitcnt lgkmcnt(4)
	v_mfma_f32_32x32x16_bf16 v[96:111], v[2:5], v[120:123], v[96:111]
	v_add3_u32 v0, v188, v177, s98
	ds_read_b128 v[120:123], v0
	v_cvt_pk_bf16_f32 v2, v48, v49
	v_cvt_pk_bf16_f32 v3, v50, v51
	v_cvt_pk_bf16_f32 v4, v52, v53
	v_cvt_pk_bf16_f32 v5, v54, v55
	s_waitcnt lgkmcnt(4)
	s_nop 0
	v_mfma_f32_32x32x16_bf16 v[80:95], v[2:5], v[124:127], v[80:95]
	ds_read_b128 v[124:127], v0 offset:8192
	s_waitcnt lgkmcnt(4)
	v_mfma_f32_32x32x16_bf16 v[96:111], v[2:5], v[12:15], v[96:111]
	v_add3_u32 v0, v189, v177, s98
	ds_read_b128 v[12:15], v0
	v_cvt_pk_bf16_f32 v2, v56, v57
	v_cvt_pk_bf16_f32 v3, v58, v59
	v_cvt_pk_bf16_f32 v4, v60, v61
	v_cvt_pk_bf16_f32 v5, v62, v63
	s_waitcnt lgkmcnt(4)
	s_nop 0
	v_mfma_f32_32x32x16_bf16 v[80:95], v[2:5], v[112:115], v[80:95]
	ds_read_b128 v[112:115], v0 offset:8192
	s_waitcnt lgkmcnt(4)
	v_mfma_f32_32x32x16_bf16 v[96:111], v[2:5], v[116:119], v[96:111]
	v_add3_u32 v0, v190, v177, s98
	ds_read_b128 v[116:119], v0
	v_cvt_pk_bf16_f32 v2, v32, v33
	v_cvt_pk_bf16_f32 v3, v34, v35
	v_cvt_pk_bf16_f32 v4, v36, v37
	v_cvt_pk_bf16_f32 v5, v38, v39
	s_waitcnt lgkmcnt(4)
	s_nop 0
	v_mfma_f32_32x32x16_bf16 v[80:95], v[2:5], v[120:123], v[80:95]
	ds_read_b128 v[120:123], v0 offset:8192
	s_waitcnt lgkmcnt(4)
	v_mfma_f32_32x32x16_bf16 v[96:111], v[2:5], v[124:127], v[96:111]
	v_add3_u32 v0, v191, v177, s98
	ds_read_b128 v[124:127], v0
	v_cvt_pk_bf16_f32 v2, v40, v41
	v_cvt_pk_bf16_f32 v3, v42, v43
	v_cvt_pk_bf16_f32 v4, v44, v45
	v_cvt_pk_bf16_f32 v5, v46, v47
	s_waitcnt lgkmcnt(4)
	s_nop 0
	v_mfma_f32_32x32x16_bf16 v[80:95], v[2:5], v[12:15], v[80:95]
	ds_read_b128 v[12:15], v0 offset:8192
	s_waitcnt lgkmcnt(4)
	v_mfma_f32_32x32x16_bf16 v[96:111], v[2:5], v[112:115], v[96:111]
	v_cvt_pk_bf16_f32 v2, v16, v17
	v_cvt_pk_bf16_f32 v3, v18, v19
	v_cvt_pk_bf16_f32 v4, v20, v21
	v_cvt_pk_bf16_f32 v5, v22, v23
	s_waitcnt lgkmcnt(3)
	s_nop 0
	v_mfma_f32_32x32x16_bf16 v[80:95], v[2:5], v[116:119], v[80:95]
	s_waitcnt lgkmcnt(2)
	v_mfma_f32_32x32x16_bf16 v[96:111], v[2:5], v[120:123], v[96:111]
	v_cvt_pk_bf16_f32 v2, v24, v25
	v_cvt_pk_bf16_f32 v3, v26, v27
	v_cvt_pk_bf16_f32 v4, v28, v29
	v_cvt_pk_bf16_f32 v5, v30, v31
	s_waitcnt lgkmcnt(1)
	s_nop 0
	v_mfma_f32_32x32x16_bf16 v[80:95], v[2:5], v[124:127], v[80:95]
	s_waitcnt lgkmcnt(0)
	v_mfma_f32_32x32x16_bf16 v[96:111], v[2:5], v[12:15], v[96:111]
.LBB0_1165:
	s_andn2_saveexec_b64 s[44:45], s[44:45]
	s_cbranch_execz .LBB0_1169
	v_mov_b32_e32 v112, 0
	v_mov_b32_e32 v113, 0
	v_mov_b32_e32 v114, 0
	v_mov_b32_e32 v115, 0
	v_mov_b32_e32 v116, 0
	v_mov_b32_e32 v117, 0
	v_mov_b32_e32 v118, 0
	v_mov_b32_e32 v119, 0
	v_mov_b32_e32 v120, 0
	v_mov_b32_e32 v121, 0
	v_mov_b32_e32 v122, 0
	v_mov_b32_e32 v123, 0
	v_mov_b32_e32 v124, 0
	v_mov_b32_e32 v125, 0
	v_mov_b32_e32 v126, 0
	v_mov_b32_e32 v127, 0
	s_and_saveexec_b64 s[60:61], s[78:79]
	s_cbranch_execz .LBB0_1168
	v_add3_u32 v0, v178, v184, s98
	ds_read_b128 v[16:19], v0
	v_add3_u32 v0, v179, v184, s98
	ds_read_b128 v[20:23], v0 offset:16384
	v_add3_u32 v0, v178, v185, s98
	ds_read_b128 v[24:27], v0
	v_add3_u32 v0, v179, v185, s98
	ds_read_b128 v[28:31], v0 offset:16384
	v_add3_u32 v0, v178, v186, s98
	ds_read_b128 v[32:35], v0
	v_add3_u32 v0, v179, v186, s98
	ds_read_b128 v[36:39], v0 offset:16384
	v_add3_u32 v0, v178, v187, s98
	ds_read_b128 v[40:43], v0
	v_add3_u32 v0, v179, v187, s98
	ds_read_b128 v[44:47], v0 offset:16384
	v_add3_u32 v0, v178, v188, s98
	ds_read_b128 v[48:51], v0
	v_add3_u32 v0, v179, v188, s98
	ds_read_b128 v[52:55], v0 offset:16384
	v_add3_u32 v0, v178, v189, s98
	ds_read_b128 v[56:59], v0
	v_add3_u32 v0, v179, v189, s98
	ds_read_b128 v[60:63], v0 offset:16384
	v_add3_u32 v0, v178, v190, s98
	ds_read_b128 v[64:67], v0
	v_add3_u32 v0, v179, v190, s98
	ds_read_b128 v[68:71], v0 offset:16384
	v_add3_u32 v0, v178, v191, s98
	ds_read_b128 v[72:75], v0
	v_add3_u32 v0, v179, v191, s98
	ds_read_b128 v[76:79], v0 offset:16384
	s_waitcnt lgkmcnt(14)
	v_mfma_f32_32x32x16_bf16 v[112:127], v[16:19], v[20:23], 0
	s_waitcnt lgkmcnt(12)
	v_mfma_f32_32x32x16_bf16 v[112:127], v[24:27], v[28:31], v[112:127]
	s_waitcnt lgkmcnt(10)
	v_mfma_f32_32x32x16_bf16 v[112:127], v[32:35], v[36:39], v[112:127]
	s_waitcnt lgkmcnt(8)
	v_mfma_f32_32x32x16_bf16 v[112:127], v[40:43], v[44:47], v[112:127]
	s_waitcnt lgkmcnt(6)
	v_mfma_f32_32x32x16_bf16 v[112:127], v[48:51], v[52:55], v[112:127]
	s_waitcnt lgkmcnt(4)
	v_mfma_f32_32x32x16_bf16 v[112:127], v[56:59], v[60:63], v[112:127]
	s_waitcnt lgkmcnt(2)
	v_mfma_f32_32x32x16_bf16 v[112:127], v[64:67], v[68:71], v[112:127]
	s_waitcnt lgkmcnt(0)
	v_mfma_f32_32x32x16_bf16 v[112:127], v[72:75], v[76:79], v[112:127]

.Lscan_b2:
	s_waitcnt lgkmcnt(0)
	s_barrier
	s_and_saveexec_b64 s[44:45], s[8:9]
	s_cbranch_execz .LBB0_1171
	v_add3_u32 v0, v180, v192, s98
	ds_read_b128 v[2:5], v0 offset:32768
	v_add_u32_e32 v0, v182, v192
	ds_read_b128 v[12:15], v0
	ds_read_b128 v[112:115], v0 offset:4096
	v_add3_u32 v0, v180, v193, s98
	ds_read_b128 v[116:119], v0 offset:32768
	v_add_u32_e32 v0, v182, v193
	ds_read_b128 v[120:123], v0
	ds_read_b128 v[124:127], v0 offset:4096
	s_ashr_i32 s81, s80, 31
	s_lshl_b64 s[60:61], s[80:81], 11
	s_waitcnt lgkmcnt(4)
	v_mfma_f32_32x32x16_bf16 v[80:95], v[2:5], v[12:15], v[80:95]
	s_waitcnt lgkmcnt(3)
	v_mfma_f32_32x32x16_bf16 v[96:111], v[2:5], v[112:115], v[96:111]
	v_add3_u32 v0, v180, v195, s98
	ds_read_b128 v[2:5], v0 offset:32768
	v_add_u32_e32 v0, v182, v195
	ds_read_b128 v[12:15], v0
	ds_read_b128 v[112:115], v0 offset:4096
	s_waitcnt lgkmcnt(4)
	v_mfma_f32_32x32x16_bf16 v[80:95], v[116:119], v[120:123], v[80:95]
	s_waitcnt lgkmcnt(3)
	v_mfma_f32_32x32x16_bf16 v[96:111], v[116:119], v[124:127], v[96:111]
	v_add3_u32 v0, v180, v196, s98
	ds_read_b128 v[116:119], v0 offset:32768
	v_add_u32_e32 v0, v182, v196
	ds_read_b128 v[120:123], v0
	ds_read_b128 v[124:127], v0 offset:4096
	s_waitcnt lgkmcnt(4)
	v_mfma_f32_32x32x16_bf16 v[80:95], v[2:5], v[12:15], v[80:95]
	s_waitcnt lgkmcnt(3)
	v_mfma_f32_32x32x16_bf16 v[96:111], v[2:5], v[112:115], v[96:111]
	s_waitcnt lgkmcnt(1)
	v_mfma_f32_32x32x16_bf16 v[80:95], v[116:119], v[120:123], v[80:95]
	s_waitcnt lgkmcnt(0)
	v_mfma_f32_32x32x16_bf16 v[96:111], v[116:119], v[124:127], v[96:111]
	v_mbcnt_lo_u32_b32 v0, -1, 0
	v_mbcnt_hi_u32_b32 v0, -1, v0
	v_and_b32_e32 v120, 31, v0
	v_lshrrev_b32_e32 v121, 5, v0
	v_mul_u32_u24_e32 v120, 0x7fe, v120
	v_mul_u32_u24_e32 v121, 0x1ff0, v121
	v_sub_u32_e32 v120, v120, v121
	v_ashrrev_i32_e32 v121, 31, v120
	v_lshl_add_u64 v[124:125], v[168:169], 0, v[120:121]
	v_lshl_add_u64 v[124:125], v[124:125], 0, s[60:61]
	s_mov_b64 s[60:61], 0x10000
	v_lshl_add_u64 v[126:127], v[124:125], 0, s[60:61]
	s_nop 3
	v_cvt_pk_bf16_f32 v80, v80, v81
	v_cvt_pk_bf16_f32 v81, v82, v83
	v_cvt_pk_bf16_f32 v82, v84, v85
	v_cvt_pk_bf16_f32 v83, v86, v87
	s_nop 1
	v_permlane32_swap_b32_e32 v80, v82
	v_permlane32_swap_b32_e32 v81, v83
	v_cvt_pk_bf16_f32 v84, v88, v89
	v_cvt_pk_bf16_f32 v85, v90, v91
	v_cvt_pk_bf16_f32 v86, v92, v93
	v_cvt_pk_bf16_f32 v87, v94, v95
	s_nop 1
	v_permlane32_swap_b32_e32 v84, v86
	v_permlane32_swap_b32_e32 v85, v87
	v_cvt_pk_bf16_f32 v88, v96, v97
	v_cvt_pk_bf16_f32 v89, v98, v99
	v_cvt_pk_bf16_f32 v90, v100, v101
	v_cvt_pk_bf16_f32 v91, v102, v103
	s_nop 1
	v_permlane32_swap_b32_e32 v88, v90
	v_permlane32_swap_b32_e32 v89, v91
	v_cvt_pk_bf16_f32 v92, v104, v105
	v_cvt_pk_bf16_f32 v93, v106, v107
	v_cvt_pk_bf16_f32 v94, v108, v109
	v_cvt_pk_bf16_f32 v95, v110, v111
	s_nop 1
	v_permlane32_swap_b32_e32 v92, v94
	v_permlane32_swap_b32_e32 v93, v95
	v_mov_b64_e32 v[96:97], v[124:125]
	v_mov_b64_e32 v[98:99], v[126:127]

.Lscan_loads_ret:
.Lscan_tail_w03:
	s_and_saveexec_b64 s[44:45], s[8:9]
	s_cbranch_execz .LBB0_1145
	v_add_u32_e32 v205, s98, v197
	v_add_u32_e32 v206, s98, v198
	v_add_u32_e32 v207, s98, v199
	v_add_u32_e32 v208, s98, v200
	v_add_u32_e32 v209, s98, v201
	v_add_u32_e32 v210, s98, v202
	v_add_u32_e32 v240, s98, v203
	v_add_u32_e32 v241, s98, v204
	v_add3_u32 v0, v180, v192, s98
	ds_read_b128 v[120:123], v0 offset:32768
	ds_read_b64_tr_b16 v[124:125], v205 offset:0
	ds_read_b64_tr_b16 v[126:127], v209 offset:1024
	ds_read_b64_tr_b16 v[12:13], v206 offset:0
	ds_read_b64_tr_b16 v[14:15], v210 offset:1024
	ds_read_b64_tr_b16 v[112:113], v207 offset:0
	ds_read_b64_tr_b16 v[114:115], v240 offset:1024
	ds_read_b64_tr_b16 v[116:117], v208 offset:0
	ds_read_b64_tr_b16 v[118:119], v241 offset:1024
	v_add3_u32 v0, v180, v193, s98
	ds_read_b128 v[2:5], v0 offset:32768
	s_waitcnt lgkmcnt(7)
	v_mfma_f32_32x32x16_bf16 v[64:79], v[124:127], v[120:123], v[64:79]
	ds_read_b64_tr_b16 v[124:125], v205 offset:4096
	ds_read_b64_tr_b16 v[126:127], v209 offset:5120
	s_waitcnt lgkmcnt(7)
	v_mfma_f32_32x32x16_bf16 v[48:63], v[12:15], v[120:123], v[48:63]
	ds_read_b64_tr_b16 v[12:13], v206 offset:4096
	ds_read_b64_tr_b16 v[14:15], v210 offset:5120
	s_waitcnt lgkmcnt(7)
	v_mfma_f32_32x32x16_bf16 v[32:47], v[112:115], v[120:123], v[32:47]
	ds_read_b64_tr_b16 v[112:113], v207 offset:4096
	ds_read_b64_tr_b16 v[114:115], v240 offset:5120
	s_waitcnt lgkmcnt(7)
	v_mfma_f32_32x32x16_bf16 v[16:31], v[116:119], v[120:123], v[16:31]
	ds_read_b64_tr_b16 v[116:117], v208 offset:4096
	ds_read_b64_tr_b16 v[118:119], v241 offset:5120
	v_add3_u32 v0, v180, v195, s98
	ds_read_b128 v[120:123], v0 offset:32768
	s_waitcnt lgkmcnt(7)
	v_mfma_f32_32x32x16_bf16 v[64:79], v[124:127], v[2:5], v[64:79]
	ds_read_b64_tr_b16 v[124:125], v205 offset:8192
	ds_read_b64_tr_b16 v[126:127], v209 offset:9216
	s_waitcnt lgkmcnt(7)
	v_mfma_f32_32x32x16_bf16 v[48:63], v[12:15], v[2:5], v[48:63]
	ds_read_b64_tr_b16 v[12:13], v206 offset:8192
	ds_read_b64_tr_b16 v[14:15], v210 offset:9216
	s_waitcnt lgkmcnt(7)
	v_mfma_f32_32x32x16_bf16 v[32:47], v[112:115], v[2:5], v[32:47]
	ds_read_b64_tr_b16 v[112:113], v207 offset:8192
	ds_read_b64_tr_b16 v[114:115], v240 offset:9216
	s_waitcnt lgkmcnt(7)
	v_mfma_f32_32x32x16_bf16 v[16:31], v[116:119], v[2:5], v[16:31]
	ds_read_b64_tr_b16 v[116:117], v208 offset:8192
	ds_read_b64_tr_b16 v[118:119], v241 offset:9216
	v_add3_u32 v0, v180, v196, s98
	ds_read_b128 v[2:5], v0 offset:32768
	s_waitcnt lgkmcnt(7)
	v_mfma_f32_32x32x16_bf16 v[64:79], v[124:127], v[120:123], v[64:79]
	ds_read_b64_tr_b16 v[124:125], v205 offset:12288
	ds_read_b64_tr_b16 v[126:127], v209 offset:13312
	s_waitcnt lgkmcnt(7)
	v_mfma_f32_32x32x16_bf16 v[48:63], v[12:15], v[120:123], v[48:63]
	ds_read_b64_tr_b16 v[12:13], v206 offset:12288
	ds_read_b64_tr_b16 v[14:15], v210 offset:13312
	s_waitcnt lgkmcnt(7)
	v_mfma_f32_32x32x16_bf16 v[32:47], v[112:115], v[120:123], v[32:47]
	ds_read_b64_tr_b16 v[112:113], v207 offset:12288
	ds_read_b64_tr_b16 v[114:115], v240 offset:13312
	s_waitcnt lgkmcnt(7)
	v_mfma_f32_32x32x16_bf16 v[16:31], v[116:119], v[120:123], v[16:31]
	ds_read_b64_tr_b16 v[116:117], v208 offset:12288
	ds_read_b64_tr_b16 v[118:119], v241 offset:13312
	s_waitcnt lgkmcnt(6)
	v_mfma_f32_32x32x16_bf16 v[64:79], v[124:127], v[2:5], v[64:79]
	s_waitcnt lgkmcnt(4)
	v_mfma_f32_32x32x16_bf16 v[48:63], v[12:15], v[2:5], v[48:63]
	s_waitcnt lgkmcnt(2)
	v_mfma_f32_32x32x16_bf16 v[32:47], v[112:115], v[2:5], v[32:47]
	s_waitcnt lgkmcnt(0)
	v_mfma_f32_32x32x16_bf16 v[16:31], v[116:119], v[2:5], v[16:31]
	s_branch .LBB0_1145
